# NA loop: 32 exec-masked bias lookups (one LDS round trip each) replaced by two groups of 16 unconditional reads + fma + cndmask (on top of MLA P.V interleave)
# baseline (speedup 1.0000x reference)
; #define ATT_SBAR() __builtin_amdgcn_sched_barrier(0)
; __device__ __forceinline__ int crow(int r, int hi) { return (r & 3) + 8 * (r >> 2) + 4 * hi; }
; #define ATT_KRD(d0_) do { const int ad_ = kbase + ATT_KO(d0_); \
;           asm volatile("ds_read_b128 %0, %1" : "=v"(fa[(d0_) % 3]) : "v"(ad_) : "memory"); \
;           asm volatile("ds_read_b128 %0, %1 offset:%2" : "=v"(fb[(d0_) % 3]) : "v"(ad_), "i"(32 * DQK * 2) : "memory"); } while (0)
; template <bool RAW>
; __device__ __forceinline__ void softmax_tile(f32x16& p0, f32x16& p1, float Cs, float& m_reg, float& l_reg, float& alpha, bf16x8& pa0, bf16x8& pa1, bf16x8& pa2, bf16x8& pa3) {
;   float pmax = fmaxf(fmaxf(p0[0], p0[1]), p1[0]);
; #pragma unroll
;   for (int r = 2; r < 16; r += 2) pmax = fmaxf(fmaxf(pmax, p0[r]), p0[r + 1]);
; #pragma unroll
;   for (int r = 1; r < 15; r += 2) pmax = fmaxf(fmaxf(pmax, p1[r]), p1[r + 1]);
;   pmax = fmaxf(pmax, p1[15]);
;   if (RAW) pmax *= Cs;
;   float mn;
;   if (__builtin_expect(__all(pmax - m_reg <= DEFER_THR * LOG2E), 1)) { mn = m_reg; alpha = 1.f; }
; template <int MODE>
; __device__ __forceinline__ void attn_unit(unsigned char* ws_, const float* rpb, const float* sink, int l, int h, int qb, int kvq, unsigned char* lds_g) {
;     ...
;         for (int d0 = 0; d0 < ND; ++d0) {
;           if (d0 + 2 < ND) { ATT_KRD(d0 + 2); asm volatile("s_waitcnt lgkmcnt(4)" ::: "memory"); }
;           else if (d0 + 1 < ND) asm volatile("s_waitcnt lgkmcnt(2)" ::: "memory");
;           else asm volatile("s_waitcnt lgkmcnt(0)" ::: "memory");
;           ATT_SBAR();
;           p0 = __builtin_amdgcn_mfma_f32_32x32x16_bf16(fa[d0 % 3], qr[d0], p0, 0, 0, 0);
;           p1 = __builtin_amdgcn_mfma_f32_32x32x16_bf16(fb[d0 % 3], qr[d0], p1, 0, 0, 0);
;           ATT_SBAR(); }
;     ...
;       }
;       ATT_SBAR();
;       if (MODE == 0) {
;         const int dr31 = (j - wrow + 7) * 31 + 15 - qcol;
; #pragma unroll
;         for (int r = 0; r < 16; ++r) { const int kc = crow(r, hi);
;           { const bool v = (kc >= c0) && (kc < c0 + 16); const float bb = rpbL[v ? dr31 + kc : 0]; p0[r] = v ? fmaf(p0[r], C, bb) : NEGM; }
;           { const int kc1 = kc + 32; const bool v = (kc1 >= c0) && (kc1 < c0 + 16); const float bb = rpbL[v ? dr31 + kc1 : 0]; p1[r] = v ? fmaf(p1[r], C, bb) : NEGM; } }
.LBB0_695:
	v_cmp_ge_u32_e32 vcc, s61, v168
	v_cmp_lt_u32_e64 s[0:1], s61, v169
	s_and_b64 s[64:65], vcc, s[0:1]
	s_and_saveexec_b64 s[0:1], s[64:65]
	s_cbranch_execz .LBB0_766
	s_lshl_b32 s64, s63, 14
	s_cmp_lg_u32 0, -1
	s_cselect_b32 s65, 0, 0
	s_add_i32 s65, s65, s64
	s_add_i32 s65, s65, 0xc000
	v_add_u32_e32 v0, s65, v160
	ds_read_b128 v[2:5], v0
	ds_read_b128 v[6:9], v0 offset:0x2000
	v_add_u32_e32 v0, s65, v161
	ds_read_b128 v[10:13], v0
	ds_read_b128 v[176:179], v0 offset:0x2000
	v_add_u32_e32 v0, s65, v162
	ds_read_b128 v[180:183], v0
	ds_read_b128 v[194:197], v0 offset:0x2000
	s_waitcnt lgkmcnt(4)
	v_mfma_f32_32x32x16_bf16 v[96:111], v[2:5], v[112:115], 0
	v_mfma_f32_32x32x16_bf16 v[80:95], v[6:9], v[112:115], 0
	v_add_u32_e32 v0, s65, v163
	ds_read_b128 v[2:5], v0
	ds_read_b128 v[6:9], v0 offset:0x2000
	s_waitcnt lgkmcnt(4)
	v_mfma_f32_32x32x16_bf16 v[96:111], v[10:13], v[116:119], v[96:111]
	v_mfma_f32_32x32x16_bf16 v[80:95], v[176:179], v[116:119], v[80:95]
	v_add_u32_e32 v0, s65, v164
	ds_read_b128 v[10:13], v0
	ds_read_b128 v[176:179], v0 offset:0x2000
	s_waitcnt lgkmcnt(4)
	v_mfma_f32_32x32x16_bf16 v[96:111], v[180:183], v[120:123], v[96:111]
	v_mfma_f32_32x32x16_bf16 v[80:95], v[194:197], v[120:123], v[80:95]
	v_add_u32_e32 v0, s65, v165
	ds_read_b128 v[180:183], v0
	ds_read_b128 v[194:197], v0 offset:0x2000
	s_waitcnt lgkmcnt(4)
	v_mfma_f32_32x32x16_bf16 v[96:111], v[2:5], v[124:127], v[96:111]
	v_mfma_f32_32x32x16_bf16 v[80:95], v[6:9], v[124:127], v[80:95]
	v_add_u32_e32 v0, s65, v166
	ds_read_b128 v[2:5], v0
	ds_read_b128 v[6:9], v0 offset:0x2000
	s_waitcnt lgkmcnt(4)
	v_mfma_f32_32x32x16_bf16 v[96:111], v[10:13], v[128:131], v[96:111]
	v_mfma_f32_32x32x16_bf16 v[80:95], v[176:179], v[128:131], v[80:95]
	v_add_u32_e32 v0, s65, v167
	ds_read_b128 v[10:13], v0
	ds_read_b128 v[176:179], v0 offset:0x2000
	s_waitcnt lgkmcnt(4)
	v_mfma_f32_32x32x16_bf16 v[96:111], v[180:183], v[132:135], v[96:111]
	v_mfma_f32_32x32x16_bf16 v[80:95], v[194:197], v[132:135], v[80:95]
	s_waitcnt lgkmcnt(2)
	v_mfma_f32_32x32x16_bf16 v[96:111], v[2:5], v[136:139], v[96:111]
	v_mfma_f32_32x32x16_bf16 v[80:95], v[6:9], v[136:139], v[80:95]
	s_waitcnt lgkmcnt(0)
	v_mfma_f32_32x32x16_bf16 v[96:111], v[10:13], v[140:143], v[96:111]
	v_mfma_f32_32x32x16_bf16 v[80:95], v[176:179], v[140:143], v[80:95]
	v_mov_b32_e32 v230, 0x3e0293ee
	v_mov_b32_e32 v231, 0xf149f2ca
	ds_read_b32 v202, v172
	ds_read_b32 v203, v172 offset:128
	ds_read_b32 v204, v172 offset:4
	ds_read_b32 v205, v172 offset:132
	ds_read_b32 v206, v172 offset:8
	ds_read_b32 v207, v172 offset:136
	ds_read_b32 v208, v172 offset:12
	ds_read_b32 v209, v172 offset:140
	ds_read_b32 v210, v172 offset:32
	ds_read_b32 v211, v172 offset:160
	ds_read_b32 v212, v172 offset:36
	ds_read_b32 v213, v172 offset:164
	ds_read_b32 v214, v172 offset:40
	ds_read_b32 v215, v172 offset:168
	ds_read_b32 v236, v172 offset:44
	ds_read_b32 v237, v172 offset:172
	s_waitcnt lgkmcnt(0)
	v_fma_f32 v2, v96, v230, v202
	v_cndmask_b32_e64 v2, v231, v2, s[6:7]
	v_fma_f32 v0, v80, v230, v203
	v_cndmask_b32_e64 v0, v231, v0, s[96:97]
	v_fma_f32 v4, v97, v230, v204
	v_cndmask_b32_e64 v4, v231, v4, s[8:9]
	v_fma_f32 v3, v81, v230, v205
	v_cndmask_b32_e64 v3, v231, v3, s[48:49]
	v_fma_f32 v6, v98, v230, v206
	v_cndmask_b32_e64 v6, v231, v6, s[10:11]
	v_fma_f32 v5, v82, v230, v207
	v_cndmask_b32_e64 v5, v231, v5, s[50:51]
	v_fma_f32 v8, v99, v230, v208
	v_cndmask_b32_e64 v8, v231, v8, s[12:13]
	v_fma_f32 v7, v83, v230, v209
	v_cndmask_b32_e64 v7, v231, v7, s[80:81]
	v_fma_f32 v10, v100, v230, v210
	v_cndmask_b32_e64 v10, v231, v10, s[14:15]
	v_fma_f32 v9, v84, v230, v211
	v_cndmask_b32_e64 v9, v231, v9, s[2:3]
	v_fma_f32 v12, v101, v230, v212
	v_cndmask_b32_e64 v12, v231, v12, s[16:17]
	v_fma_f32 v11, v85, v230, v213
	v_cndmask_b32_e64 v11, v231, v11, s[70:71]
	v_fma_f32 v80, v102, v230, v214
	v_cndmask_b32_e64 v80, v231, v80, s[18:19]
	v_fma_f32 v13, v86, v230, v215
	v_cndmask_b32_e64 v13, v231, v13, s[52:53]
	v_fma_f32 v82, v103, v230, v236
	v_cndmask_b32_e64 v82, v231, v82, s[20:21]
	v_fma_f32 v81, v87, v230, v237
	v_cndmask_b32_e64 v81, v231, v81, s[44:45]
	ds_read_b32 v238, v172 offset:64
	ds_read_b32 v239, v172 offset:192
	ds_read_b32 v240, v172 offset:68
	ds_read_b32 v241, v172 offset:196
	ds_read_b32 v242, v172 offset:72
	ds_read_b32 v243, v172 offset:200
	ds_read_b32 v244, v172 offset:76
	ds_read_b32 v245, v172 offset:204
	ds_read_b32 v246, v172 offset:96
	ds_read_b32 v247, v172 offset:224
	ds_read_b32 v248, v172 offset:100
	ds_read_b32 v249, v172 offset:228
	ds_read_b32 v250, v172 offset:104
	ds_read_b32 v251, v172 offset:232
	ds_read_b32 v252, v172 offset:108
	ds_read_b32 v253, v172 offset:236
	s_waitcnt lgkmcnt(0)
	v_fma_f32 v98, v104, v230, v238
	v_cndmask_b32_e64 v98, v231, v98, s[46:47]
	v_fma_f32 v83, v88, v230, v239
	v_cndmask_b32_e64 v83, v231, v83, s[22:23]
	v_fma_f32 v99, v105, v230, v240
	v_cndmask_b32_e64 v99, v231, v99, s[72:73]
	v_fma_f32 v101, v89, v230, v241
	v_cndmask_b32_e64 v101, v231, v101, s[24:25]
	v_fma_f32 v102, v106, v230, v242
	v_cndmask_b32_e64 v102, v231, v102, s[40:41]
	v_fma_f32 v103, v90, v230, v243
	v_cndmask_b32_e64 v103, v231, v103, s[26:27]
	v_fma_f32 v106, v107, v230, v244
	v_cndmask_b32_e64 v106, v231, v106, s[82:83]
	v_fma_f32 v105, v91, v230, v245
	v_cndmask_b32_e64 v105, v231, v105, s[28:29]
	v_fma_f32 v156, v108, v230, v246
	v_cndmask_b32_e64 v156, v231, v156, s[84:85]
	v_fma_f32 v107, v92, v230, v247
	v_cndmask_b32_e64 v107, v231, v107, s[30:31]
	v_fma_f32 v176, v109, v230, v248
	v_cndmask_b32_e64 v176, v231, v176, s[78:79]
	v_fma_f32 v157, v93, v230, v249
	v_cndmask_b32_e64 v157, v231, v157, s[34:35]
	v_fma_f32 v178, v110, v230, v250
	v_cndmask_b32_e64 v178, v231, v178, s[68:69]
	v_fma_f32 v177, v94, v230, v251
	v_cndmask_b32_e64 v177, v231, v177, s[36:37]
	v_fma_f32 v180, v111, v230, v252
	v_cndmask_b32_e64 v180, v231, v180, s[88:89]
	v_fma_f32 v179, v95, v230, v253
	v_cndmask_b32_e64 v179, v231, v179, s[38:39]
	v_max_f32_e32 v14, v4, v4
	v_max_f32_e32 v15, v2, v2
	v_max_f32_e32 v14, v15, v14
	v_max3_f32 v14, v14, v0, v6
	v_max3_f32 v14, v14, v8, v10
	v_max3_f32 v14, v14, v12, v80
	v_max3_f32 v14, v14, v82, v98
	v_max3_f32 v14, v14, v99, v102
	v_max3_f32 v14, v14, v106, v156
	v_max3_f32 v14, v14, v176, v178
	v_max3_f32 v14, v14, v180, v3
	v_max3_f32 v14, v14, v5, v7
	v_max3_f32 v14, v14, v9, v11
	v_max3_f32 v14, v14, v13, v81
	v_max3_f32 v14, v14, v83, v101
	v_max3_f32 v14, v14, v103, v105
	v_max3_f32 v14, v14, v107, v157
	v_max3_f32 v14, v14, v177, v179
	v_sub_f32_e32 v15, v14, v173
	v_cmp_ge_f32_e32 vcc, s54, v15
	s_cmp_lg_u64 vcc, exec
	v_mov_b32_e32 v175, 1.0
	s_cbranch_scc1 .LBB0_770
